# FoX unit epilogue: dropped the post-loop workgroup barrier (the epilogue touches no LDS; the barrier after the stores already fences the ring and the bias table for the next unit)
# speedup vs baseline: 1.0041x; 1.0041x over previous
; __device__ __forceinline__ unsigned pk_bf16(float lo, float hi) { return pg8::cvt_pk_bf16(lo, hi); }
; template <int DV, int NMAP>
; __device__ __forceinline__ void attn_unit(LAS unsigned char* lds, const bf16_t* U, bf16_t* MIX, const float* logf, int b, int h, int qb, float lam, float slope2, const float* gn, float outscale, const int tid) {
;     ...
;     __syncthreads();
;     const float inv = 1.0f / (l_run + __shfl_xor(l_run, 32));
;     const size_t orow = (rowbase + qrow0 + r32) * DM;
;     if (NMAP == 1) {
; #pragma unroll
;         for (int d = 0; d < NDB; ++d)
; #pragma unroll
;             for (int g = 0; g < 4; ++g) { u32x2 w; w.x = pk_bf16(o[d][4 * g] * inv, o[d][4 * g + 1] * inv); w.y = pk_bf16(o[d][4 * g + 2] * inv, o[d][4 * g + 3] * inv);
;                 *(u32x2*)(MIX + orow + 64 * h + 32 * d + 8 * g + 4 * hi) = w; }
;         __syncthreads();
.LBB0_205:
	ds_bpermute_b32 v0, v224, v105
	s_lshl_b32 s20, s33, 1
	s_waitcnt lgkmcnt(0)
	v_add_f32_e32 v0, v105, v0
	v_div_scale_f32 v34, s[30:31], v0, v0, 1.0
	v_rcp_f32_e32 v35, v34
	v_div_scale_f32 v36, vcc, 1.0, v0, 1.0
	v_readlane_b32 s30, v250, 34
	v_fma_f32 v37, -v34, v35, 1.0
	v_fmac_f32_e32 v35, v37, v35
	v_mul_f32_e32 v37, v36, v35
	v_fma_f32 v38, -v34, v37, v36
	v_fmac_f32_e32 v37, v38, v35
	v_fma_f32 v34, -v34, v37, v36
	v_div_fmas_f32 v34, v34, v35, v37
	v_readlane_b32 s31, v250, 35
	s_add_u32 s30, s30, s20
	v_div_fixup_f32 v36, v34, v0, 1.0
	s_addc_u32 s31, s31, 0
	v_lshlrev_b64 v[34:35], 11, v[98:99]
	v_lshl_add_u64 v[34:35], s[30:31], 0, v[34:35]
	v_lshlrev_b32_e32 v0, 1, v130
	v_lshl_add_u64 v[34:35], v[34:35], 0, v[0:1]
	v_lshl_add_u64 v[34:35], v[34:35], 0, v[0:1]
	v_mul_f32_e32 v56, v2, v36
	v_mul_f32_e32 v57, v3, v36
	v_cvt_pk_bf16_f32 v40, v56, v57
	v_mul_f32_e32 v56, v4, v36
	v_mul_f32_e32 v57, v5, v36
	v_cvt_pk_bf16_f32 v41, v56, v57
	v_mul_f32_e32 v56, v6, v36
	v_mul_f32_e32 v57, v7, v36
	v_cvt_pk_bf16_f32 v42, v56, v57
	v_mul_f32_e32 v56, v8, v36
	v_mul_f32_e32 v57, v9, v36
	v_cvt_pk_bf16_f32 v43, v56, v57
	s_nop 1
	v_permlane32_swap_b32_e32 v40, v42
	v_permlane32_swap_b32_e32 v41, v43
	global_store_dwordx4 v[34:35], v[40:43], off
	v_mul_f32_e32 v56, v10, v36
	v_mul_f32_e32 v57, v11, v36
	v_cvt_pk_bf16_f32 v44, v56, v57
	v_mul_f32_e32 v56, v12, v36
	v_mul_f32_e32 v57, v13, v36
	v_cvt_pk_bf16_f32 v45, v56, v57
	v_mul_f32_e32 v56, v14, v36
	v_mul_f32_e32 v57, v15, v36
	v_cvt_pk_bf16_f32 v46, v56, v57
	v_mul_f32_e32 v56, v16, v36
	v_mul_f32_e32 v57, v17, v36
	v_cvt_pk_bf16_f32 v47, v56, v57
	s_nop 1
	v_permlane32_swap_b32_e32 v44, v46
	v_permlane32_swap_b32_e32 v45, v47
	global_store_dwordx4 v[34:35], v[44:47], off offset:32
	v_mul_f32_e32 v56, v18, v36
	v_mul_f32_e32 v57, v19, v36
	v_cvt_pk_bf16_f32 v48, v56, v57
	v_mul_f32_e32 v56, v20, v36
	v_mul_f32_e32 v57, v21, v36
	v_cvt_pk_bf16_f32 v49, v56, v57
	v_mul_f32_e32 v56, v22, v36
	v_mul_f32_e32 v57, v23, v36
	v_cvt_pk_bf16_f32 v50, v56, v57
	v_mul_f32_e32 v56, v24, v36
	v_mul_f32_e32 v57, v25, v36
	v_cvt_pk_bf16_f32 v51, v56, v57
	s_nop 1
	v_permlane32_swap_b32_e32 v48, v50
	v_permlane32_swap_b32_e32 v49, v51
	global_store_dwordx4 v[34:35], v[48:51], off offset:64
	v_mul_f32_e32 v56, v26, v36
	v_mul_f32_e32 v57, v27, v36
	v_cvt_pk_bf16_f32 v52, v56, v57
	v_mul_f32_e32 v56, v28, v36
	v_mul_f32_e32 v57, v29, v36
	v_cvt_pk_bf16_f32 v53, v56, v57
	v_mul_f32_e32 v56, v30, v36
	v_mul_f32_e32 v57, v31, v36
	v_cvt_pk_bf16_f32 v54, v56, v57
	v_mul_f32_e32 v56, v32, v36
	v_mul_f32_e32 v57, v33, v36
	v_cvt_pk_bf16_f32 v55, v56, v57
	s_nop 1
	v_permlane32_swap_b32_e32 v52, v54
	v_permlane32_swap_b32_e32 v53, v55
	global_store_dwordx4 v[34:35], v[52:55], off offset:96
	s_mov_b64 s[30:31], 0
	s_barrier
